# lnmod phases 9/12/20: hand-written token loop (modulation loads before prefetch, counted waits, 10 consecutive tokens per wave)
# speedup vs baseline: 1.0173x; 1.0009x over previous
.Lln9_entry:
	s_waitcnt vmcnt(0) lgkmcnt(0)
	v_readlane_b32 s98, v246, 10
	v_readlane_b32 s99, v246, 11
	s_nop 4
	v_and_b32_e32 v66, 63, v226
	v_lshlrev_b32_e32 v74, 3, v66
	v_lshlrev_b32_e32 v66, 4, v66
	v_mov_b32_e32 v67, 0
	v_mov_b32_e32 v75, 0
	v_mov_b32_e32 v65, 0x1000
	v_mov_b32_e32 v101, 0x800
	s_load_dwordx2 s[100:101], s[98:99], 0x120
	s_waitcnt lgkmcnt(0)
	v_mov_b32_e32 v118, s100
	v_mov_b32_e32 v119, s101
	v_lshl_add_u64 v[118:119], v[118:119], 0, v[66:67]
	s_load_dwordx2 s[100:101], s[98:99], 0x1a8
	s_waitcnt lgkmcnt(0)
	v_mov_b32_e32 v120, s100
	v_mov_b32_e32 v121, s101
	v_lshl_add_u64 v[120:121], v[120:121], 0, v[74:75]
	s_load_dwordx2 s[100:101], s[98:99], 0x128
	s_waitcnt lgkmcnt(0)
	s_add_u32 s100, s100, 0x3000
	s_addc_u32 s101, s101, 0
	v_mov_b32_e32 v122, s100
	v_mov_b32_e32 v123, s101
	v_lshl_add_u64 v[122:123], v[122:123], 0, v[66:67]
	v_readfirstlane_b32 s100, v64
	s_mov_b32 s101, 1
	s_nop 3
	s_cmp_eq_u32 s6, 0x800
	s_cbranch_scc0 .Lln9_strided
	s_mul_i32 s100, s100, 10
	s_mov_b32 s101, 3
.Lln9_strided:
	v_mov_b32_e32 v142, s100
	v_mad_u64_u32 v[128:129], vcc, v142, v65, v[118:119]
	global_load_dwordx4 v[32:35], v[128:129], off offset:0
	global_load_dwordx4 v[36:39], v[128:129], off offset:1024
	global_load_dwordx4 v[40:43], v[128:129], off offset:2048
	global_load_dwordx4 v[44:47], v[128:129], off offset:3072
.Lln9_top:
	s_sub_u32 s98, s100, 0x1000
	s_lshr_b32 s98, s98, 12
	s_add_u32 s98, s98, 1
	s_cmp_gt_u32 s100, 0xfff
	s_cselect_b32 s98, s98, 0
	s_mul_i32 s98, s98, 0x6000
	s_mov_b32 s99, 0
	v_lshl_add_u64 v[130:131], v[122:123], 0, s[98:99]
	s_movk_i32 s98, 0x1000
	v_lshl_add_u64 v[132:133], v[130:131], 0, s[98:99]
	global_load_dwordx4 v[70:73], v[130:131], off offset:0
	global_load_dwordx4 v[86:89], v[130:131], off offset:1024
	global_load_dwordx4 v[90:93], v[130:131], off offset:2048
	global_load_dwordx4 v[94:97], v[130:131], off offset:3072
	global_load_dwordx4 v[102:105], v[132:133], off offset:0
	global_load_dwordx4 v[106:109], v[132:133], off offset:1024
	global_load_dwordx4 v[110:113], v[132:133], off offset:2048
	global_load_dwordx4 v[114:117], v[132:133], off offset:3072
	s_bitcmp1_b32 s101, 1
	s_cselect_b32 s98, 1, s6
	s_add_u32 s98, s100, s98
	s_min_u32 s98, s98, 0x4fff
	v_mov_b32_e32 v143, s98
	v_mad_u64_u32 v[128:129], vcc, v143, v65, v[118:119]
	global_load_dwordx4 v[48:51], v[128:129], off offset:0
	global_load_dwordx4 v[52:55], v[128:129], off offset:1024
	global_load_dwordx4 v[56:59], v[128:129], off offset:2048
	global_load_dwordx4 v[60:63], v[128:129], off offset:3072
	s_bitcmp0_b32 s101, 0
	s_cbranch_scc1 .Lln9_w2
	s_waitcnt vmcnt(12)
	s_and_b32 s101, s101, 2
	s_branch .Lln9_w3
.Lln9_w2:
	s_waitcnt vmcnt(20)
.Lln9_w3:
	v_pk_add_f32 v[134:135], v[32:33], v[34:35]
	v_pk_add_f32 v[134:135], v[134:135], v[36:37]
	v_pk_add_f32 v[134:135], v[134:135], v[38:39]
	v_pk_add_f32 v[134:135], v[134:135], v[40:41]
	v_pk_add_f32 v[134:135], v[134:135], v[42:43]
	v_pk_add_f32 v[134:135], v[134:135], v[44:45]
	v_pk_add_f32 v[134:135], v[134:135], v[46:47]
	v_add_f32_e32 v134, v134, v135
	s_nop 1
	v_add_f32_dpp v134, v134, v134 row_ror:8 row_mask:0xf bank_mask:0xf bound_ctrl:1
	s_nop 1
	v_add_f32_dpp v134, v134, v134 row_ror:4 row_mask:0xf bank_mask:0xf bound_ctrl:1
	s_nop 1
	v_add_f32_dpp v134, v134, v134 row_ror:2 row_mask:0xf bank_mask:0xf bound_ctrl:1
	s_nop 1
	v_add_f32_dpp v134, v134, v134 row_ror:1 row_mask:0xf bank_mask:0xf bound_ctrl:1
	s_nop 0
	v_readlane_b32 s98, v134, 0
	v_readlane_b32 s99, v134, 16
	s_nop 0
	v_mov_b32_e32 v136, s98
	s_nop 0
	v_add_f32_e32 v136, s99, v136
	v_readlane_b32 s98, v134, 32
	v_readlane_b32 s99, v134, 48
	s_nop 0
	v_add_f32_e32 v136, s98, v136
	s_nop 0
	v_add_f32_e32 v134, s99, v136
	v_mul_f32_e32 v138, 0x3a800000, v134
	v_pk_add_f32 v[32:33], v[32:33], v[138:139] op_sel_hi:[1,0] neg_lo:[0,1] neg_hi:[0,1]
	v_pk_add_f32 v[34:35], v[34:35], v[138:139] op_sel_hi:[1,0] neg_lo:[0,1] neg_hi:[0,1]
	v_pk_add_f32 v[36:37], v[36:37], v[138:139] op_sel_hi:[1,0] neg_lo:[0,1] neg_hi:[0,1]
	v_pk_add_f32 v[38:39], v[38:39], v[138:139] op_sel_hi:[1,0] neg_lo:[0,1] neg_hi:[0,1]
	v_pk_add_f32 v[40:41], v[40:41], v[138:139] op_sel_hi:[1,0] neg_lo:[0,1] neg_hi:[0,1]
	v_pk_add_f32 v[42:43], v[42:43], v[138:139] op_sel_hi:[1,0] neg_lo:[0,1] neg_hi:[0,1]
	v_pk_add_f32 v[44:45], v[44:45], v[138:139] op_sel_hi:[1,0] neg_lo:[0,1] neg_hi:[0,1]
	v_pk_add_f32 v[46:47], v[46:47], v[138:139] op_sel_hi:[1,0] neg_lo:[0,1] neg_hi:[0,1]
	v_pk_mul_f32 v[134:135], v[32:33], v[32:33]
	v_pk_fma_f32 v[134:135], v[34:35], v[34:35], v[134:135]
	v_pk_fma_f32 v[134:135], v[36:37], v[36:37], v[134:135]
	v_pk_fma_f32 v[134:135], v[38:39], v[38:39], v[134:135]
	v_pk_fma_f32 v[134:135], v[40:41], v[40:41], v[134:135]
	v_pk_fma_f32 v[134:135], v[42:43], v[42:43], v[134:135]
	v_pk_fma_f32 v[134:135], v[44:45], v[44:45], v[134:135]
	v_pk_fma_f32 v[134:135], v[46:47], v[46:47], v[134:135]
	v_add_f32_e32 v134, v134, v135
	s_nop 1
	v_add_f32_dpp v134, v134, v134 row_ror:8 row_mask:0xf bank_mask:0xf bound_ctrl:1
	s_nop 1
	v_add_f32_dpp v134, v134, v134 row_ror:4 row_mask:0xf bank_mask:0xf bound_ctrl:1
	s_nop 1
	v_add_f32_dpp v134, v134, v134 row_ror:2 row_mask:0xf bank_mask:0xf bound_ctrl:1
	s_nop 1
	v_add_f32_dpp v134, v134, v134 row_ror:1 row_mask:0xf bank_mask:0xf bound_ctrl:1
	s_nop 0
	v_readlane_b32 s98, v134, 0
	v_readlane_b32 s99, v134, 16
	s_nop 0
	v_mov_b32_e32 v136, s98
	s_nop 0
	v_add_f32_e32 v136, s99, v136
	v_readlane_b32 s98, v134, 32
	v_readlane_b32 s99, v134, 48
	s_nop 0
	v_add_f32_e32 v136, s98, v136
	s_nop 0
	v_add_f32_e32 v134, s99, v136
	v_mov_b32_e32 v136, 0x3727c5ac
	v_fmac_f32_e32 v136, 0x3a800000, v134
	v_rsq_f32_e32 v140, v136
	s_nop 0
	v_pk_mul_f32 v[32:33], v[32:33], v[140:141] op_sel_hi:[1,0]
	v_pk_mul_f32 v[34:35], v[34:35], v[140:141] op_sel_hi:[1,0]
	v_pk_mul_f32 v[36:37], v[36:37], v[140:141] op_sel_hi:[1,0]
	v_pk_mul_f32 v[38:39], v[38:39], v[140:141] op_sel_hi:[1,0]
	v_pk_mul_f32 v[40:41], v[40:41], v[140:141] op_sel_hi:[1,0]
	v_pk_mul_f32 v[42:43], v[42:43], v[140:141] op_sel_hi:[1,0]
	v_pk_mul_f32 v[44:45], v[44:45], v[140:141] op_sel_hi:[1,0]
	v_pk_mul_f32 v[46:47], v[46:47], v[140:141] op_sel_hi:[1,0]
	v_pk_fma_f32 v[32:33], v[0:1], v[32:33], v[4:5]
	v_pk_fma_f32 v[34:35], v[2:3], v[34:35], v[6:7]
	v_pk_fma_f32 v[36:37], v[8:9], v[36:37], v[12:13]
	v_pk_fma_f32 v[38:39], v[10:11], v[38:39], v[14:15]
	v_pk_fma_f32 v[40:41], v[16:17], v[40:41], v[20:21]
	v_pk_fma_f32 v[42:43], v[18:19], v[42:43], v[22:23]
	v_pk_fma_f32 v[44:45], v[24:25], v[44:45], v[28:29]
	v_pk_fma_f32 v[46:47], v[26:27], v[46:47], v[30:31]
	v_mad_u64_u32 v[128:129], vcc, v142, v65, v[118:119]
	global_store_dwordx4 v[128:129], v[32:35], off offset:0
	global_store_dwordx4 v[128:129], v[36:39], off offset:1024
	global_store_dwordx4 v[128:129], v[40:43], off offset:2048
	global_store_dwordx4 v[128:129], v[44:47], off offset:3072
	s_waitcnt vmcnt(8)
	v_mad_u64_u32 v[128:129], vcc, v142, v101, v[120:121]
	v_pk_add_f32 v[102:103], v[102:103], 1.0 op_sel_hi:[1,0]
	v_pk_add_f32 v[104:105], v[104:105], 1.0 op_sel_hi:[1,0]
	v_pk_fma_f32 v[102:103], v[102:103], v[32:33], v[70:71]
	v_pk_fma_f32 v[104:105], v[104:105], v[34:35], v[72:73]
	v_cvt_pk_bf16_f32 v144, v102, v103
	v_cvt_pk_bf16_f32 v145, v104, v105
	global_store_dwordx2 v[128:129], v[144:145], off offset:0
	v_pk_add_f32 v[106:107], v[106:107], 1.0 op_sel_hi:[1,0]
	v_pk_add_f32 v[108:109], v[108:109], 1.0 op_sel_hi:[1,0]
	v_pk_fma_f32 v[106:107], v[106:107], v[36:37], v[86:87]
	v_pk_fma_f32 v[108:109], v[108:109], v[38:39], v[88:89]
	v_cvt_pk_bf16_f32 v146, v106, v107
	v_cvt_pk_bf16_f32 v147, v108, v109
	global_store_dwordx2 v[128:129], v[146:147], off offset:512
	v_pk_add_f32 v[110:111], v[110:111], 1.0 op_sel_hi:[1,0]
	v_pk_add_f32 v[112:113], v[112:113], 1.0 op_sel_hi:[1,0]
	v_pk_fma_f32 v[110:111], v[110:111], v[40:41], v[90:91]
	v_pk_fma_f32 v[112:113], v[112:113], v[42:43], v[92:93]
	v_cvt_pk_bf16_f32 v148, v110, v111
	v_cvt_pk_bf16_f32 v149, v112, v113
	global_store_dwordx2 v[128:129], v[148:149], off offset:1024
	v_pk_add_f32 v[114:115], v[114:115], 1.0 op_sel_hi:[1,0]
	v_pk_add_f32 v[116:117], v[116:117], 1.0 op_sel_hi:[1,0]
	v_pk_fma_f32 v[114:115], v[114:115], v[44:45], v[94:95]
	v_pk_fma_f32 v[116:117], v[116:117], v[46:47], v[96:97]
	v_cvt_pk_bf16_f32 v150, v114, v115
	v_cvt_pk_bf16_f32 v151, v116, v117
	global_store_dwordx2 v[128:129], v[150:151], off offset:1536
	s_bitcmp1_b32 s101, 1
	s_cselect_b32 s98, 1, s6
	s_add_u32 s100, s100, s98
	v_mov_b32_e32 v142, s100
	s_bitcmp1_b32 s101, 1
	s_cbranch_scc0 .Lln9_ck0
	s_mul_hi_u32 s98, s100, 0xcccccccd
	s_lshr_b32 s98, s98, 3
	s_mul_i32 s98, s98, 10
	s_cmp_lg_u32 s98, s100
	s_branch .Lln9_cd0
.Lln9_ck0:
	s_cmp_lt_u32 s100, 0x5000
.Lln9_cd0:
	s_cbranch_scc0 .Lln9_done
	s_sub_u32 s98, s100, 0x1000
	s_lshr_b32 s98, s98, 12
	s_add_u32 s98, s98, 1
	s_cmp_gt_u32 s100, 0xfff
	s_cselect_b32 s98, s98, 0
	s_mul_i32 s98, s98, 0x6000
	s_mov_b32 s99, 0
	v_lshl_add_u64 v[130:131], v[122:123], 0, s[98:99]
	s_movk_i32 s98, 0x1000
	v_lshl_add_u64 v[132:133], v[130:131], 0, s[98:99]
	global_load_dwordx4 v[70:73], v[130:131], off offset:0
	global_load_dwordx4 v[86:89], v[130:131], off offset:1024
	global_load_dwordx4 v[90:93], v[130:131], off offset:2048
	global_load_dwordx4 v[94:97], v[130:131], off offset:3072
	global_load_dwordx4 v[102:105], v[132:133], off offset:0
	global_load_dwordx4 v[106:109], v[132:133], off offset:1024
	global_load_dwordx4 v[110:113], v[132:133], off offset:2048
	global_load_dwordx4 v[114:117], v[132:133], off offset:3072
	s_bitcmp1_b32 s101, 1
	s_cselect_b32 s98, 1, s6
	s_add_u32 s98, s100, s98
	s_min_u32 s98, s98, 0x4fff
	v_mov_b32_e32 v143, s98
	v_mad_u64_u32 v[128:129], vcc, v143, v65, v[118:119]
	global_load_dwordx4 v[32:35], v[128:129], off offset:0
	global_load_dwordx4 v[36:39], v[128:129], off offset:1024
	global_load_dwordx4 v[40:43], v[128:129], off offset:2048
	global_load_dwordx4 v[44:47], v[128:129], off offset:3072
	s_waitcnt vmcnt(20)
	v_pk_add_f32 v[134:135], v[48:49], v[50:51]
	v_pk_add_f32 v[134:135], v[134:135], v[52:53]
	v_pk_add_f32 v[134:135], v[134:135], v[54:55]
	v_pk_add_f32 v[134:135], v[134:135], v[56:57]
	v_pk_add_f32 v[134:135], v[134:135], v[58:59]
	v_pk_add_f32 v[134:135], v[134:135], v[60:61]
	v_pk_add_f32 v[134:135], v[134:135], v[62:63]
	v_add_f32_e32 v134, v134, v135
	s_nop 1
	v_add_f32_dpp v134, v134, v134 row_ror:8 row_mask:0xf bank_mask:0xf bound_ctrl:1
	s_nop 1
	v_add_f32_dpp v134, v134, v134 row_ror:4 row_mask:0xf bank_mask:0xf bound_ctrl:1
	s_nop 1
	v_add_f32_dpp v134, v134, v134 row_ror:2 row_mask:0xf bank_mask:0xf bound_ctrl:1
	s_nop 1
	v_add_f32_dpp v134, v134, v134 row_ror:1 row_mask:0xf bank_mask:0xf bound_ctrl:1
	s_nop 0
	v_readlane_b32 s98, v134, 0
	v_readlane_b32 s99, v134, 16
	s_nop 0
	v_mov_b32_e32 v136, s98
	s_nop 0
	v_add_f32_e32 v136, s99, v136
	v_readlane_b32 s98, v134, 32
	v_readlane_b32 s99, v134, 48
	s_nop 0
	v_add_f32_e32 v136, s98, v136
	s_nop 0
	v_add_f32_e32 v134, s99, v136
	v_mul_f32_e32 v138, 0x3a800000, v134
	v_pk_add_f32 v[48:49], v[48:49], v[138:139] op_sel_hi:[1,0] neg_lo:[0,1] neg_hi:[0,1]
	v_pk_add_f32 v[50:51], v[50:51], v[138:139] op_sel_hi:[1,0] neg_lo:[0,1] neg_hi:[0,1]
	v_pk_add_f32 v[52:53], v[52:53], v[138:139] op_sel_hi:[1,0] neg_lo:[0,1] neg_hi:[0,1]
	v_pk_add_f32 v[54:55], v[54:55], v[138:139] op_sel_hi:[1,0] neg_lo:[0,1] neg_hi:[0,1]
	v_pk_add_f32 v[56:57], v[56:57], v[138:139] op_sel_hi:[1,0] neg_lo:[0,1] neg_hi:[0,1]
	v_pk_add_f32 v[58:59], v[58:59], v[138:139] op_sel_hi:[1,0] neg_lo:[0,1] neg_hi:[0,1]
	v_pk_add_f32 v[60:61], v[60:61], v[138:139] op_sel_hi:[1,0] neg_lo:[0,1] neg_hi:[0,1]
	v_pk_add_f32 v[62:63], v[62:63], v[138:139] op_sel_hi:[1,0] neg_lo:[0,1] neg_hi:[0,1]
	v_pk_mul_f32 v[134:135], v[48:49], v[48:49]
	v_pk_fma_f32 v[134:135], v[50:51], v[50:51], v[134:135]
	v_pk_fma_f32 v[134:135], v[52:53], v[52:53], v[134:135]
	v_pk_fma_f32 v[134:135], v[54:55], v[54:55], v[134:135]
	v_pk_fma_f32 v[134:135], v[56:57], v[56:57], v[134:135]
	v_pk_fma_f32 v[134:135], v[58:59], v[58:59], v[134:135]
	v_pk_fma_f32 v[134:135], v[60:61], v[60:61], v[134:135]
	v_pk_fma_f32 v[134:135], v[62:63], v[62:63], v[134:135]
	v_add_f32_e32 v134, v134, v135
	s_nop 1
	v_add_f32_dpp v134, v134, v134 row_ror:8 row_mask:0xf bank_mask:0xf bound_ctrl:1
	s_nop 1
	v_add_f32_dpp v134, v134, v134 row_ror:4 row_mask:0xf bank_mask:0xf bound_ctrl:1
	s_nop 1
	v_add_f32_dpp v134, v134, v134 row_ror:2 row_mask:0xf bank_mask:0xf bound_ctrl:1
	s_nop 1
	v_add_f32_dpp v134, v134, v134 row_ror:1 row_mask:0xf bank_mask:0xf bound_ctrl:1
	s_nop 0
	v_readlane_b32 s98, v134, 0
	v_readlane_b32 s99, v134, 16
	s_nop 0
	v_mov_b32_e32 v136, s98
	s_nop 0
	v_add_f32_e32 v136, s99, v136
	v_readlane_b32 s98, v134, 32
	v_readlane_b32 s99, v134, 48
	s_nop 0
	v_add_f32_e32 v136, s98, v136
	s_nop 0
	v_add_f32_e32 v134, s99, v136
	v_mov_b32_e32 v136, 0x3727c5ac
	v_fmac_f32_e32 v136, 0x3a800000, v134
	v_rsq_f32_e32 v140, v136
	s_nop 0
	v_pk_mul_f32 v[48:49], v[48:49], v[140:141] op_sel_hi:[1,0]
	v_pk_mul_f32 v[50:51], v[50:51], v[140:141] op_sel_hi:[1,0]
	v_pk_mul_f32 v[52:53], v[52:53], v[140:141] op_sel_hi:[1,0]
	v_pk_mul_f32 v[54:55], v[54:55], v[140:141] op_sel_hi:[1,0]
	v_pk_mul_f32 v[56:57], v[56:57], v[140:141] op_sel_hi:[1,0]
	v_pk_mul_f32 v[58:59], v[58:59], v[140:141] op_sel_hi:[1,0]
	v_pk_mul_f32 v[60:61], v[60:61], v[140:141] op_sel_hi:[1,0]
	v_pk_mul_f32 v[62:63], v[62:63], v[140:141] op_sel_hi:[1,0]
	v_pk_fma_f32 v[48:49], v[0:1], v[48:49], v[4:5]
	v_pk_fma_f32 v[50:51], v[2:3], v[50:51], v[6:7]
	v_pk_fma_f32 v[52:53], v[8:9], v[52:53], v[12:13]
	v_pk_fma_f32 v[54:55], v[10:11], v[54:55], v[14:15]
	v_pk_fma_f32 v[56:57], v[16:17], v[56:57], v[20:21]
	v_pk_fma_f32 v[58:59], v[18:19], v[58:59], v[22:23]
	v_pk_fma_f32 v[60:61], v[24:25], v[60:61], v[28:29]
	v_pk_fma_f32 v[62:63], v[26:27], v[62:63], v[30:31]
	v_mad_u64_u32 v[128:129], vcc, v142, v65, v[118:119]
	global_store_dwordx4 v[128:129], v[48:51], off offset:0
	global_store_dwordx4 v[128:129], v[52:55], off offset:1024
	global_store_dwordx4 v[128:129], v[56:59], off offset:2048
	global_store_dwordx4 v[128:129], v[60:63], off offset:3072
	s_waitcnt vmcnt(8)
	v_mad_u64_u32 v[128:129], vcc, v142, v101, v[120:121]
	v_pk_add_f32 v[102:103], v[102:103], 1.0 op_sel_hi:[1,0]
	v_pk_add_f32 v[104:105], v[104:105], 1.0 op_sel_hi:[1,0]
	v_pk_fma_f32 v[102:103], v[102:103], v[48:49], v[70:71]
	v_pk_fma_f32 v[104:105], v[104:105], v[50:51], v[72:73]
	v_cvt_pk_bf16_f32 v144, v102, v103
	v_cvt_pk_bf16_f32 v145, v104, v105
	global_store_dwordx2 v[128:129], v[144:145], off offset:0
	v_pk_add_f32 v[106:107], v[106:107], 1.0 op_sel_hi:[1,0]
	v_pk_add_f32 v[108:109], v[108:109], 1.0 op_sel_hi:[1,0]
	v_pk_fma_f32 v[106:107], v[106:107], v[52:53], v[86:87]
	v_pk_fma_f32 v[108:109], v[108:109], v[54:55], v[88:89]
	v_cvt_pk_bf16_f32 v146, v106, v107
	v_cvt_pk_bf16_f32 v147, v108, v109
	global_store_dwordx2 v[128:129], v[146:147], off offset:512
	v_pk_add_f32 v[110:111], v[110:111], 1.0 op_sel_hi:[1,0]
	v_pk_add_f32 v[112:113], v[112:113], 1.0 op_sel_hi:[1,0]
	v_pk_fma_f32 v[110:111], v[110:111], v[56:57], v[90:91]
	v_pk_fma_f32 v[112:113], v[112:113], v[58:59], v[92:93]
	v_cvt_pk_bf16_f32 v148, v110, v111
	v_cvt_pk_bf16_f32 v149, v112, v113
	global_store_dwordx2 v[128:129], v[148:149], off offset:1024
	v_pk_add_f32 v[114:115], v[114:115], 1.0 op_sel_hi:[1,0]
	v_pk_add_f32 v[116:117], v[116:117], 1.0 op_sel_hi:[1,0]
	v_pk_fma_f32 v[114:115], v[114:115], v[60:61], v[94:95]
	v_pk_fma_f32 v[116:117], v[116:117], v[62:63], v[96:97]
	v_cvt_pk_bf16_f32 v150, v114, v115
	v_cvt_pk_bf16_f32 v151, v116, v117
	global_store_dwordx2 v[128:129], v[150:151], off offset:1536
	s_bitcmp1_b32 s101, 1
	s_cselect_b32 s98, 1, s6
	s_add_u32 s100, s100, s98
	v_mov_b32_e32 v142, s100
	s_bitcmp1_b32 s101, 1
	s_cbranch_scc0 .Lln9_ck1
	s_mul_hi_u32 s98, s100, 0xcccccccd
	s_lshr_b32 s98, s98, 3
	s_mul_i32 s98, s98, 10
	s_cmp_lg_u32 s98, s100
	s_branch .Lln9_cd1

.Lln9_cd1:
	s_cbranch_scc1 .Lln9_top
.Lln9_done:
	s_branch .LBB0_1465
.LBB0_1465:
	s_or_b64 exec, exec, s[4:5]
	s_waitcnt vmcnt(0)
	s_barrier
	s_and_saveexec_b64 s[0:1], s[72:73]
	s_cbranch_execz .LBB0_1517
	v_mov_b32_e32 v0, 0x12000
	s_waitcnt vmcnt(0) expcnt(0) lgkmcnt(0)
	ds_read_b32 v2, v0
	v_mov_b32_e32 v0, 0x12004
	ds_read_b32 v0, v0
	s_waitcnt lgkmcnt(1)
	v_cmp_ne_u32_e32 vcc, 0, v2
	s_cbranch_vccnz .LBB0_1481
	s_add_u32 s4, s80, 0x1000
	s_addc_u32 s5, s81, 0
	s_add_u32 s6, s80, 0x1100
	s_addc_u32 s7, s81, 0
	s_add_u32 s8, s80, 0x1200
	s_addc_u32 s9, s81, 0
	s_mul_i32 s2, s77, s78
	s_add_u32 s10, s80, 0x1300
	s_mul_i32 s2, s2, s76
	s_addc_u32 s11, s81, 0
	s_mov_b32 s3, 1
	v_mov_b32_e32 v16, 0
	s_branch .LBB0_1469

.Lln12_entry:
	s_waitcnt vmcnt(0) lgkmcnt(0)
	v_readlane_b32 s98, v246, 10
	v_readlane_b32 s99, v246, 11
	s_nop 4
	v_and_b32_e32 v66, 63, v226
	v_lshlrev_b32_e32 v74, 3, v66
	v_lshlrev_b32_e32 v66, 4, v66
	v_mov_b32_e32 v67, 0
	v_mov_b32_e32 v75, 0
	v_mov_b32_e32 v65, 0x1000
	v_mov_b32_e32 v99, 0x800
	s_load_dwordx2 s[100:101], s[98:99], 0x120
	s_waitcnt lgkmcnt(0)
	v_mov_b32_e32 v94, s100
	v_mov_b32_e32 v95, s101
	v_lshl_add_u64 v[94:95], v[94:95], 0, v[66:67]
	s_load_dwordx2 s[100:101], s[98:99], 0x1a8
	s_waitcnt lgkmcnt(0)
	v_mov_b32_e32 v120, s100
	v_mov_b32_e32 v121, s101
	v_lshl_add_u64 v[120:121], v[120:121], 0, v[74:75]
	s_load_dwordx2 s[100:101], s[98:99], 0x128
	s_waitcnt lgkmcnt(0)
	s_add_u32 s100, s100, 0x1e000
	s_addc_u32 s101, s101, 0
	v_mov_b32_e32 v122, s100
	v_mov_b32_e32 v123, s101
	v_lshl_add_u64 v[122:123], v[122:123], 0, v[66:67]
	v_readfirstlane_b32 s100, v64
	s_mov_b32 s101, 1
	s_nop 3
	s_cmp_eq_u32 s6, 0x800
	s_cbranch_scc0 .Lln12_strided
	s_mul_i32 s100, s100, 10
	s_mov_b32 s101, 3
.Lln12_strided:
	v_mov_b32_e32 v142, s100
	v_mad_u64_u32 v[128:129], vcc, v142, v65, v[94:95]
	global_load_dwordx4 v[32:35], v[128:129], off offset:0
	global_load_dwordx4 v[36:39], v[128:129], off offset:1024
	global_load_dwordx4 v[40:43], v[128:129], off offset:2048
	global_load_dwordx4 v[44:47], v[128:129], off offset:3072
.Lln12_top:
	s_sub_u32 s98, s100, 0x1000
	s_lshr_b32 s98, s98, 12
	s_add_u32 s98, s98, 1
	s_cmp_gt_u32 s100, 0xfff
	s_cselect_b32 s98, s98, 0
	s_mul_i32 s98, s98, 0x6000
	s_mov_b32 s99, 0
	v_lshl_add_u64 v[130:131], v[122:123], 0, s[98:99]
	s_movk_i32 s98, 0x1000
	v_lshl_add_u64 v[132:133], v[130:131], 0, s[98:99]
	global_load_dwordx4 v[70:73], v[130:131], off offset:0
	global_load_dwordx4 v[86:89], v[130:131], off offset:1024
	global_load_dwordx4 v[90:93], v[130:131], off offset:2048
	global_load_dwordx4 v[100:103], v[130:131], off offset:3072
	global_load_dwordx4 v[104:107], v[132:133], off offset:0
	global_load_dwordx4 v[108:111], v[132:133], off offset:1024
	global_load_dwordx4 v[112:115], v[132:133], off offset:2048
	global_load_dwordx4 v[116:119], v[132:133], off offset:3072
	s_bitcmp1_b32 s101, 1
	s_cselect_b32 s98, 1, s6
	s_add_u32 s98, s100, s98
	s_min_u32 s98, s98, 0x4fff
	v_mov_b32_e32 v143, s98
	v_mad_u64_u32 v[128:129], vcc, v143, v65, v[94:95]
	global_load_dwordx4 v[48:51], v[128:129], off offset:0
	global_load_dwordx4 v[52:55], v[128:129], off offset:1024
	global_load_dwordx4 v[56:59], v[128:129], off offset:2048
	global_load_dwordx4 v[60:63], v[128:129], off offset:3072
	s_bitcmp0_b32 s101, 0
	s_cbranch_scc1 .Lln12_w2
	s_waitcnt vmcnt(12)
	s_and_b32 s101, s101, 2
	s_branch .Lln12_w3

.Lln12_w3:
	v_pk_add_f32 v[134:135], v[32:33], v[34:35]
	v_pk_add_f32 v[134:135], v[134:135], v[36:37]
	v_pk_add_f32 v[134:135], v[134:135], v[38:39]
	v_pk_add_f32 v[134:135], v[134:135], v[40:41]
	v_pk_add_f32 v[134:135], v[134:135], v[42:43]
	v_pk_add_f32 v[134:135], v[134:135], v[44:45]
	v_pk_add_f32 v[134:135], v[134:135], v[46:47]
	v_add_f32_e32 v134, v134, v135
	s_nop 1
	v_add_f32_dpp v134, v134, v134 row_ror:8 row_mask:0xf bank_mask:0xf bound_ctrl:1
	s_nop 1
	v_add_f32_dpp v134, v134, v134 row_ror:4 row_mask:0xf bank_mask:0xf bound_ctrl:1
	s_nop 1
	v_add_f32_dpp v134, v134, v134 row_ror:2 row_mask:0xf bank_mask:0xf bound_ctrl:1
	s_nop 1
	v_add_f32_dpp v134, v134, v134 row_ror:1 row_mask:0xf bank_mask:0xf bound_ctrl:1
	s_nop 0
	v_readlane_b32 s98, v134, 0
	v_readlane_b32 s99, v134, 16
	s_nop 0
	v_mov_b32_e32 v136, s98
	s_nop 0
	v_add_f32_e32 v136, s99, v136
	v_readlane_b32 s98, v134, 32
	v_readlane_b32 s99, v134, 48
	s_nop 0
	v_add_f32_e32 v136, s98, v136
	s_nop 0
	v_add_f32_e32 v134, s99, v136
	v_mul_f32_e32 v138, 0x3a800000, v134
	v_pk_add_f32 v[32:33], v[32:33], v[138:139] op_sel_hi:[1,0] neg_lo:[0,1] neg_hi:[0,1]
	v_pk_add_f32 v[34:35], v[34:35], v[138:139] op_sel_hi:[1,0] neg_lo:[0,1] neg_hi:[0,1]
	v_pk_add_f32 v[36:37], v[36:37], v[138:139] op_sel_hi:[1,0] neg_lo:[0,1] neg_hi:[0,1]
	v_pk_add_f32 v[38:39], v[38:39], v[138:139] op_sel_hi:[1,0] neg_lo:[0,1] neg_hi:[0,1]
	v_pk_add_f32 v[40:41], v[40:41], v[138:139] op_sel_hi:[1,0] neg_lo:[0,1] neg_hi:[0,1]
	v_pk_add_f32 v[42:43], v[42:43], v[138:139] op_sel_hi:[1,0] neg_lo:[0,1] neg_hi:[0,1]
	v_pk_add_f32 v[44:45], v[44:45], v[138:139] op_sel_hi:[1,0] neg_lo:[0,1] neg_hi:[0,1]
	v_pk_add_f32 v[46:47], v[46:47], v[138:139] op_sel_hi:[1,0] neg_lo:[0,1] neg_hi:[0,1]
	v_pk_mul_f32 v[134:135], v[32:33], v[32:33]
	v_pk_fma_f32 v[134:135], v[34:35], v[34:35], v[134:135]
	v_pk_fma_f32 v[134:135], v[36:37], v[36:37], v[134:135]
	v_pk_fma_f32 v[134:135], v[38:39], v[38:39], v[134:135]
	v_pk_fma_f32 v[134:135], v[40:41], v[40:41], v[134:135]
	v_pk_fma_f32 v[134:135], v[42:43], v[42:43], v[134:135]
	v_pk_fma_f32 v[134:135], v[44:45], v[44:45], v[134:135]
	v_pk_fma_f32 v[134:135], v[46:47], v[46:47], v[134:135]
	v_add_f32_e32 v134, v134, v135
	s_nop 1
	v_add_f32_dpp v134, v134, v134 row_ror:8 row_mask:0xf bank_mask:0xf bound_ctrl:1
	s_nop 1
	v_add_f32_dpp v134, v134, v134 row_ror:4 row_mask:0xf bank_mask:0xf bound_ctrl:1
	s_nop 1
	v_add_f32_dpp v134, v134, v134 row_ror:2 row_mask:0xf bank_mask:0xf bound_ctrl:1
	s_nop 1
	v_add_f32_dpp v134, v134, v134 row_ror:1 row_mask:0xf bank_mask:0xf bound_ctrl:1
	s_nop 0
	v_readlane_b32 s98, v134, 0
	v_readlane_b32 s99, v134, 16
	s_nop 0
	v_mov_b32_e32 v136, s98
	s_nop 0
	v_add_f32_e32 v136, s99, v136
	v_readlane_b32 s98, v134, 32
	v_readlane_b32 s99, v134, 48
	s_nop 0
	v_add_f32_e32 v136, s98, v136
	s_nop 0
	v_add_f32_e32 v134, s99, v136
	v_mov_b32_e32 v136, 0x3727c5ac
	v_fmac_f32_e32 v136, 0x3a800000, v134
	v_rsq_f32_e32 v140, v136
	s_nop 0
	v_pk_mul_f32 v[32:33], v[32:33], v[140:141] op_sel_hi:[1,0]
	v_pk_mul_f32 v[34:35], v[34:35], v[140:141] op_sel_hi:[1,0]
	v_pk_mul_f32 v[36:37], v[36:37], v[140:141] op_sel_hi:[1,0]
	v_pk_mul_f32 v[38:39], v[38:39], v[140:141] op_sel_hi:[1,0]
	v_pk_mul_f32 v[40:41], v[40:41], v[140:141] op_sel_hi:[1,0]
	v_pk_mul_f32 v[42:43], v[42:43], v[140:141] op_sel_hi:[1,0]
	v_pk_mul_f32 v[44:45], v[44:45], v[140:141] op_sel_hi:[1,0]
	v_pk_mul_f32 v[46:47], v[46:47], v[140:141] op_sel_hi:[1,0]
	v_pk_fma_f32 v[32:33], v[0:1], v[32:33], v[4:5]
	v_pk_fma_f32 v[34:35], v[2:3], v[34:35], v[6:7]
	v_pk_fma_f32 v[36:37], v[8:9], v[36:37], v[12:13]
	v_pk_fma_f32 v[38:39], v[10:11], v[38:39], v[14:15]
	v_pk_fma_f32 v[40:41], v[16:17], v[40:41], v[20:21]
	v_pk_fma_f32 v[42:43], v[18:19], v[42:43], v[22:23]
	v_pk_fma_f32 v[44:45], v[24:25], v[44:45], v[28:29]
	v_pk_fma_f32 v[46:47], v[26:27], v[46:47], v[30:31]
	v_mad_u64_u32 v[128:129], vcc, v142, v65, v[94:95]
	global_store_dwordx4 v[128:129], v[32:35], off offset:0
	global_store_dwordx4 v[128:129], v[36:39], off offset:1024
	global_store_dwordx4 v[128:129], v[40:43], off offset:2048
	global_store_dwordx4 v[128:129], v[44:47], off offset:3072
	s_waitcnt vmcnt(8)
	v_mad_u64_u32 v[128:129], vcc, v142, v99, v[120:121]
	v_pk_add_f32 v[104:105], v[104:105], 1.0 op_sel_hi:[1,0]
	v_pk_add_f32 v[106:107], v[106:107], 1.0 op_sel_hi:[1,0]
	v_pk_fma_f32 v[104:105], v[104:105], v[32:33], v[70:71]
	v_pk_fma_f32 v[106:107], v[106:107], v[34:35], v[72:73]
	v_cvt_pk_bf16_f32 v144, v104, v105
	v_cvt_pk_bf16_f32 v145, v106, v107
	global_store_dwordx2 v[128:129], v[144:145], off offset:0
	v_pk_add_f32 v[108:109], v[108:109], 1.0 op_sel_hi:[1,0]
	v_pk_add_f32 v[110:111], v[110:111], 1.0 op_sel_hi:[1,0]
	v_pk_fma_f32 v[108:109], v[108:109], v[36:37], v[86:87]
	v_pk_fma_f32 v[110:111], v[110:111], v[38:39], v[88:89]
	v_cvt_pk_bf16_f32 v146, v108, v109
	v_cvt_pk_bf16_f32 v147, v110, v111
	global_store_dwordx2 v[128:129], v[146:147], off offset:512
	v_pk_add_f32 v[112:113], v[112:113], 1.0 op_sel_hi:[1,0]
	v_pk_add_f32 v[114:115], v[114:115], 1.0 op_sel_hi:[1,0]
	v_pk_fma_f32 v[112:113], v[112:113], v[40:41], v[90:91]
	v_pk_fma_f32 v[114:115], v[114:115], v[42:43], v[92:93]
	v_cvt_pk_bf16_f32 v148, v112, v113
	v_cvt_pk_bf16_f32 v149, v114, v115
	global_store_dwordx2 v[128:129], v[148:149], off offset:1024
	v_pk_add_f32 v[116:117], v[116:117], 1.0 op_sel_hi:[1,0]
	v_pk_add_f32 v[118:119], v[118:119], 1.0 op_sel_hi:[1,0]
	v_pk_fma_f32 v[116:117], v[116:117], v[44:45], v[100:101]
	v_pk_fma_f32 v[118:119], v[118:119], v[46:47], v[102:103]
	v_cvt_pk_bf16_f32 v150, v116, v117
	v_cvt_pk_bf16_f32 v151, v118, v119
	global_store_dwordx2 v[128:129], v[150:151], off offset:1536
	s_bitcmp1_b32 s101, 1
	s_cselect_b32 s98, 1, s6
	s_add_u32 s100, s100, s98
	v_mov_b32_e32 v142, s100
	s_bitcmp1_b32 s101, 1
	s_cbranch_scc0 .Lln12_ck0
	s_mul_hi_u32 s98, s100, 0xcccccccd
	s_lshr_b32 s98, s98, 3
	s_mul_i32 s98, s98, 10
	s_cmp_lg_u32 s98, s100
	s_branch .Lln12_cd0

.Lln12_cd0:
	s_cbranch_scc0 .Lln12_done
	s_sub_u32 s98, s100, 0x1000
	s_lshr_b32 s98, s98, 12
	s_add_u32 s98, s98, 1
	s_cmp_gt_u32 s100, 0xfff
	s_cselect_b32 s98, s98, 0
	s_mul_i32 s98, s98, 0x6000
	s_mov_b32 s99, 0
	v_lshl_add_u64 v[130:131], v[122:123], 0, s[98:99]
	s_movk_i32 s98, 0x1000
	v_lshl_add_u64 v[132:133], v[130:131], 0, s[98:99]
	global_load_dwordx4 v[70:73], v[130:131], off offset:0
	global_load_dwordx4 v[86:89], v[130:131], off offset:1024
	global_load_dwordx4 v[90:93], v[130:131], off offset:2048
	global_load_dwordx4 v[100:103], v[130:131], off offset:3072
	global_load_dwordx4 v[104:107], v[132:133], off offset:0
	global_load_dwordx4 v[108:111], v[132:133], off offset:1024
	global_load_dwordx4 v[112:115], v[132:133], off offset:2048
	global_load_dwordx4 v[116:119], v[132:133], off offset:3072
	s_bitcmp1_b32 s101, 1
	s_cselect_b32 s98, 1, s6
	s_add_u32 s98, s100, s98
	s_min_u32 s98, s98, 0x4fff
	v_mov_b32_e32 v143, s98
	v_mad_u64_u32 v[128:129], vcc, v143, v65, v[94:95]
	global_load_dwordx4 v[32:35], v[128:129], off offset:0
	global_load_dwordx4 v[36:39], v[128:129], off offset:1024
	global_load_dwordx4 v[40:43], v[128:129], off offset:2048
	global_load_dwordx4 v[44:47], v[128:129], off offset:3072
	s_waitcnt vmcnt(20)
	v_pk_add_f32 v[134:135], v[48:49], v[50:51]
	v_pk_add_f32 v[134:135], v[134:135], v[52:53]
	v_pk_add_f32 v[134:135], v[134:135], v[54:55]
	v_pk_add_f32 v[134:135], v[134:135], v[56:57]
	v_pk_add_f32 v[134:135], v[134:135], v[58:59]
	v_pk_add_f32 v[134:135], v[134:135], v[60:61]
	v_pk_add_f32 v[134:135], v[134:135], v[62:63]
	v_add_f32_e32 v134, v134, v135
	s_nop 1
	v_add_f32_dpp v134, v134, v134 row_ror:8 row_mask:0xf bank_mask:0xf bound_ctrl:1
	s_nop 1
	v_add_f32_dpp v134, v134, v134 row_ror:4 row_mask:0xf bank_mask:0xf bound_ctrl:1
	s_nop 1
	v_add_f32_dpp v134, v134, v134 row_ror:2 row_mask:0xf bank_mask:0xf bound_ctrl:1
	s_nop 1
	v_add_f32_dpp v134, v134, v134 row_ror:1 row_mask:0xf bank_mask:0xf bound_ctrl:1
	s_nop 0
	v_readlane_b32 s98, v134, 0
	v_readlane_b32 s99, v134, 16
	s_nop 0
	v_mov_b32_e32 v136, s98
	s_nop 0
	v_add_f32_e32 v136, s99, v136
	v_readlane_b32 s98, v134, 32
	v_readlane_b32 s99, v134, 48
	s_nop 0
	v_add_f32_e32 v136, s98, v136
	s_nop 0
	v_add_f32_e32 v134, s99, v136
	v_mul_f32_e32 v138, 0x3a800000, v134
	v_pk_add_f32 v[48:49], v[48:49], v[138:139] op_sel_hi:[1,0] neg_lo:[0,1] neg_hi:[0,1]
	v_pk_add_f32 v[50:51], v[50:51], v[138:139] op_sel_hi:[1,0] neg_lo:[0,1] neg_hi:[0,1]
	v_pk_add_f32 v[52:53], v[52:53], v[138:139] op_sel_hi:[1,0] neg_lo:[0,1] neg_hi:[0,1]
	v_pk_add_f32 v[54:55], v[54:55], v[138:139] op_sel_hi:[1,0] neg_lo:[0,1] neg_hi:[0,1]
	v_pk_add_f32 v[56:57], v[56:57], v[138:139] op_sel_hi:[1,0] neg_lo:[0,1] neg_hi:[0,1]
	v_pk_add_f32 v[58:59], v[58:59], v[138:139] op_sel_hi:[1,0] neg_lo:[0,1] neg_hi:[0,1]
	v_pk_add_f32 v[60:61], v[60:61], v[138:139] op_sel_hi:[1,0] neg_lo:[0,1] neg_hi:[0,1]
	v_pk_add_f32 v[62:63], v[62:63], v[138:139] op_sel_hi:[1,0] neg_lo:[0,1] neg_hi:[0,1]
	v_pk_mul_f32 v[134:135], v[48:49], v[48:49]
	v_pk_fma_f32 v[134:135], v[50:51], v[50:51], v[134:135]
	v_pk_fma_f32 v[134:135], v[52:53], v[52:53], v[134:135]
	v_pk_fma_f32 v[134:135], v[54:55], v[54:55], v[134:135]
	v_pk_fma_f32 v[134:135], v[56:57], v[56:57], v[134:135]
	v_pk_fma_f32 v[134:135], v[58:59], v[58:59], v[134:135]
	v_pk_fma_f32 v[134:135], v[60:61], v[60:61], v[134:135]
	v_pk_fma_f32 v[134:135], v[62:63], v[62:63], v[134:135]
	v_add_f32_e32 v134, v134, v135
	s_nop 1
	v_add_f32_dpp v134, v134, v134 row_ror:8 row_mask:0xf bank_mask:0xf bound_ctrl:1
	s_nop 1
	v_add_f32_dpp v134, v134, v134 row_ror:4 row_mask:0xf bank_mask:0xf bound_ctrl:1
	s_nop 1
	v_add_f32_dpp v134, v134, v134 row_ror:2 row_mask:0xf bank_mask:0xf bound_ctrl:1
	s_nop 1
	v_add_f32_dpp v134, v134, v134 row_ror:1 row_mask:0xf bank_mask:0xf bound_ctrl:1
	s_nop 0
	v_readlane_b32 s98, v134, 0
	v_readlane_b32 s99, v134, 16
	s_nop 0
	v_mov_b32_e32 v136, s98
	s_nop 0
	v_add_f32_e32 v136, s99, v136
	v_readlane_b32 s98, v134, 32
	v_readlane_b32 s99, v134, 48
	s_nop 0
	v_add_f32_e32 v136, s98, v136
	s_nop 0
	v_add_f32_e32 v134, s99, v136
	v_mov_b32_e32 v136, 0x3727c5ac
	v_fmac_f32_e32 v136, 0x3a800000, v134
	v_rsq_f32_e32 v140, v136
	s_nop 0
	v_pk_mul_f32 v[48:49], v[48:49], v[140:141] op_sel_hi:[1,0]
	v_pk_mul_f32 v[50:51], v[50:51], v[140:141] op_sel_hi:[1,0]
	v_pk_mul_f32 v[52:53], v[52:53], v[140:141] op_sel_hi:[1,0]
	v_pk_mul_f32 v[54:55], v[54:55], v[140:141] op_sel_hi:[1,0]
	v_pk_mul_f32 v[56:57], v[56:57], v[140:141] op_sel_hi:[1,0]
	v_pk_mul_f32 v[58:59], v[58:59], v[140:141] op_sel_hi:[1,0]
	v_pk_mul_f32 v[60:61], v[60:61], v[140:141] op_sel_hi:[1,0]
	v_pk_mul_f32 v[62:63], v[62:63], v[140:141] op_sel_hi:[1,0]
	v_pk_fma_f32 v[48:49], v[0:1], v[48:49], v[4:5]
	v_pk_fma_f32 v[50:51], v[2:3], v[50:51], v[6:7]
	v_pk_fma_f32 v[52:53], v[8:9], v[52:53], v[12:13]
	v_pk_fma_f32 v[54:55], v[10:11], v[54:55], v[14:15]
	v_pk_fma_f32 v[56:57], v[16:17], v[56:57], v[20:21]
	v_pk_fma_f32 v[58:59], v[18:19], v[58:59], v[22:23]
	v_pk_fma_f32 v[60:61], v[24:25], v[60:61], v[28:29]
	v_pk_fma_f32 v[62:63], v[26:27], v[62:63], v[30:31]
	v_mad_u64_u32 v[128:129], vcc, v142, v65, v[94:95]
	global_store_dwordx4 v[128:129], v[48:51], off offset:0
	global_store_dwordx4 v[128:129], v[52:55], off offset:1024
	global_store_dwordx4 v[128:129], v[56:59], off offset:2048
	global_store_dwordx4 v[128:129], v[60:63], off offset:3072
	s_waitcnt vmcnt(8)
	v_mad_u64_u32 v[128:129], vcc, v142, v99, v[120:121]
	v_pk_add_f32 v[104:105], v[104:105], 1.0 op_sel_hi:[1,0]
	v_pk_add_f32 v[106:107], v[106:107], 1.0 op_sel_hi:[1,0]
	v_pk_fma_f32 v[104:105], v[104:105], v[48:49], v[70:71]
	v_pk_fma_f32 v[106:107], v[106:107], v[50:51], v[72:73]
	v_cvt_pk_bf16_f32 v144, v104, v105
	v_cvt_pk_bf16_f32 v145, v106, v107
	global_store_dwordx2 v[128:129], v[144:145], off offset:0
	v_pk_add_f32 v[108:109], v[108:109], 1.0 op_sel_hi:[1,0]
	v_pk_add_f32 v[110:111], v[110:111], 1.0 op_sel_hi:[1,0]
	v_pk_fma_f32 v[108:109], v[108:109], v[52:53], v[86:87]
	v_pk_fma_f32 v[110:111], v[110:111], v[54:55], v[88:89]
	v_cvt_pk_bf16_f32 v146, v108, v109
	v_cvt_pk_bf16_f32 v147, v110, v111
	global_store_dwordx2 v[128:129], v[146:147], off offset:512
	v_pk_add_f32 v[112:113], v[112:113], 1.0 op_sel_hi:[1,0]
	v_pk_add_f32 v[114:115], v[114:115], 1.0 op_sel_hi:[1,0]
	v_pk_fma_f32 v[112:113], v[112:113], v[56:57], v[90:91]
	v_pk_fma_f32 v[114:115], v[114:115], v[58:59], v[92:93]
	v_cvt_pk_bf16_f32 v148, v112, v113
	v_cvt_pk_bf16_f32 v149, v114, v115
	global_store_dwordx2 v[128:129], v[148:149], off offset:1024
	v_pk_add_f32 v[116:117], v[116:117], 1.0 op_sel_hi:[1,0]
	v_pk_add_f32 v[118:119], v[118:119], 1.0 op_sel_hi:[1,0]
	v_pk_fma_f32 v[116:117], v[116:117], v[60:61], v[100:101]
	v_pk_fma_f32 v[118:119], v[118:119], v[62:63], v[102:103]
	v_cvt_pk_bf16_f32 v150, v116, v117
	v_cvt_pk_bf16_f32 v151, v118, v119
	global_store_dwordx2 v[128:129], v[150:151], off offset:1536
	s_bitcmp1_b32 s101, 1
	s_cselect_b32 s98, 1, s6
	s_add_u32 s100, s100, s98
	v_mov_b32_e32 v142, s100
	s_bitcmp1_b32 s101, 1
	s_cbranch_scc0 .Lln12_ck1
	s_mul_hi_u32 s98, s100, 0xcccccccd
	s_lshr_b32 s98, s98, 3
	s_mul_i32 s98, s98, 10
	s_cmp_lg_u32 s98, s100
	s_branch .Lln12_cd1

.Lln12_done:
	s_branch .LBB0_1636
.LBB0_1636:
	s_or_b64 exec, exec, s[4:5]
	s_waitcnt vmcnt(0)
	s_barrier
	s_and_saveexec_b64 s[0:1], s[72:73]
	s_cbranch_execz .LBB0_1688
	v_mov_b32_e32 v0, 0x12000
	s_waitcnt vmcnt(0) expcnt(0) lgkmcnt(0)
	ds_read_b32 v2, v0
	v_mov_b32_e32 v0, 0x12004
	ds_read_b32 v0, v0
	s_waitcnt lgkmcnt(1)
	v_cmp_ne_u32_e32 vcc, 0, v2
	s_cbranch_vccnz .LBB0_1652
	s_add_u32 s4, s80, 0x1000
	s_addc_u32 s5, s81, 0
	s_add_u32 s6, s80, 0x1100
	s_addc_u32 s7, s81, 0
	s_add_u32 s8, s80, 0x1200
	s_addc_u32 s9, s81, 0
	s_mul_i32 s2, s77, s78
	s_add_u32 s10, s80, 0x1300
	s_mul_i32 s2, s2, s76
	s_addc_u32 s11, s81, 0
	s_mov_b32 s3, 1
	v_mov_b32_e32 v16, 0
	s_branch .LBB0_1640

.Lln20_entry:
	s_waitcnt vmcnt(0) lgkmcnt(0)
	v_readlane_b32 s98, v246, 10
	v_readlane_b32 s99, v246, 11
	s_nop 4
	v_and_b32_e32 v70, 63, v226
	v_lshlrev_b32_e32 v114, 3, v70
	v_lshlrev_b32_e32 v70, 4, v70
	v_mov_b32_e32 v71, 0
	v_mov_b32_e32 v115, 0
	v_mov_b32_e32 v140, 0x1000
	v_mov_b32_e32 v141, 0x800
	s_load_dwordx2 s[100:101], s[98:99], 0x120
	s_waitcnt lgkmcnt(0)
	v_mov_b32_e32 v116, s100
	v_mov_b32_e32 v117, s101
	v_lshl_add_u64 v[116:117], v[116:117], 0, v[70:71]
	s_load_dwordx2 s[100:101], s[98:99], 0x1a8
	s_waitcnt lgkmcnt(0)
	v_mov_b32_e32 v118, s100
	v_mov_b32_e32 v119, s101
	v_lshl_add_u64 v[118:119], v[118:119], 0, v[114:115]
	s_load_dwordx2 s[100:101], s[98:99], 0x128
	s_waitcnt lgkmcnt(0)
	s_add_u32 s100, s100, 0x21000
	s_addc_u32 s101, s101, 0
	v_mov_b32_e32 v120, s100
	v_mov_b32_e32 v121, s101
	v_lshl_add_u64 v[120:121], v[120:121], 0, v[70:71]
	v_readfirstlane_b32 s100, v82
	s_mov_b32 s101, 1
	s_nop 3
	s_cmp_eq_u32 s6, 0x800
	s_cbranch_scc0 .Lln20_strided
	s_mul_i32 s100, s100, 10
	s_mov_b32 s101, 3
.Lln20_strided:
	v_mov_b32_e32 v142, s100
	v_mad_u64_u32 v[126:127], vcc, v142, v140, v[116:117]
	global_load_dwordx4 v[32:35], v[126:127], off offset:0
	global_load_dwordx4 v[36:39], v[126:127], off offset:1024
	global_load_dwordx4 v[40:43], v[126:127], off offset:2048
	global_load_dwordx4 v[44:47], v[126:127], off offset:3072
.Lln20_top:
	s_sub_u32 s98, s100, 0x1000
	s_lshr_b32 s98, s98, 12
	s_add_u32 s98, s98, 1
	s_cmp_gt_u32 s100, 0xfff
	s_cselect_b32 s98, s98, 0
	s_mul_i32 s98, s98, 0x6000
	s_mov_b32 s99, 0
	v_lshl_add_u64 v[128:129], v[120:121], 0, s[98:99]
	s_movk_i32 s98, 0x1000
	v_lshl_add_u64 v[130:131], v[128:129], 0, s[98:99]
	global_load_dwordx4 v[66:69], v[128:129], off offset:0
	global_load_dwordx4 v[86:89], v[128:129], off offset:1024
	global_load_dwordx4 v[90:93], v[128:129], off offset:2048
	global_load_dwordx4 v[94:97], v[128:129], off offset:3072
	global_load_dwordx4 v[98:101], v[130:131], off offset:0
	global_load_dwordx4 v[102:105], v[130:131], off offset:1024
	global_load_dwordx4 v[106:109], v[130:131], off offset:2048
	global_load_dwordx4 v[110:113], v[130:131], off offset:3072
	s_bitcmp1_b32 s101, 1
	s_cselect_b32 s98, 1, s6
	s_add_u32 s98, s100, s98
	s_min_u32 s98, s98, 0x4fff
	v_mov_b32_e32 v143, s98
	v_mad_u64_u32 v[126:127], vcc, v143, v140, v[116:117]
	global_load_dwordx4 v[48:51], v[126:127], off offset:0
	global_load_dwordx4 v[52:55], v[126:127], off offset:1024
	global_load_dwordx4 v[56:59], v[126:127], off offset:2048
	global_load_dwordx4 v[60:63], v[126:127], off offset:3072
	s_bitcmp0_b32 s101, 0
	s_cbranch_scc1 .Lln20_w2
	s_waitcnt vmcnt(12)
	s_and_b32 s101, s101, 2
	s_branch .Lln20_w3

.Lln20_w3:
	v_pk_add_f32 v[132:133], v[32:33], v[34:35]
	v_pk_add_f32 v[132:133], v[132:133], v[36:37]
	v_pk_add_f32 v[132:133], v[132:133], v[38:39]
	v_pk_add_f32 v[132:133], v[132:133], v[40:41]
	v_pk_add_f32 v[132:133], v[132:133], v[42:43]
	v_pk_add_f32 v[132:133], v[132:133], v[44:45]
	v_pk_add_f32 v[132:133], v[132:133], v[46:47]
	v_add_f32_e32 v132, v132, v133
	s_nop 1
	v_add_f32_dpp v132, v132, v132 row_ror:8 row_mask:0xf bank_mask:0xf bound_ctrl:1
	s_nop 1
	v_add_f32_dpp v132, v132, v132 row_ror:4 row_mask:0xf bank_mask:0xf bound_ctrl:1
	s_nop 1
	v_add_f32_dpp v132, v132, v132 row_ror:2 row_mask:0xf bank_mask:0xf bound_ctrl:1
	s_nop 1
	v_add_f32_dpp v132, v132, v132 row_ror:1 row_mask:0xf bank_mask:0xf bound_ctrl:1
	s_nop 0
	v_readlane_b32 s98, v132, 0
	v_readlane_b32 s99, v132, 16
	s_nop 0
	v_mov_b32_e32 v134, s98
	s_nop 0
	v_add_f32_e32 v134, s99, v134
	v_readlane_b32 s98, v132, 32
	v_readlane_b32 s99, v132, 48
	s_nop 0
	v_add_f32_e32 v134, s98, v134
	s_nop 0
	v_add_f32_e32 v132, s99, v134
	v_mul_f32_e32 v136, 0x3a800000, v132
	v_pk_add_f32 v[32:33], v[32:33], v[136:137] op_sel_hi:[1,0] neg_lo:[0,1] neg_hi:[0,1]
	v_pk_add_f32 v[34:35], v[34:35], v[136:137] op_sel_hi:[1,0] neg_lo:[0,1] neg_hi:[0,1]
	v_pk_add_f32 v[36:37], v[36:37], v[136:137] op_sel_hi:[1,0] neg_lo:[0,1] neg_hi:[0,1]
	v_pk_add_f32 v[38:39], v[38:39], v[136:137] op_sel_hi:[1,0] neg_lo:[0,1] neg_hi:[0,1]
	v_pk_add_f32 v[40:41], v[40:41], v[136:137] op_sel_hi:[1,0] neg_lo:[0,1] neg_hi:[0,1]
	v_pk_add_f32 v[42:43], v[42:43], v[136:137] op_sel_hi:[1,0] neg_lo:[0,1] neg_hi:[0,1]
	v_pk_add_f32 v[44:45], v[44:45], v[136:137] op_sel_hi:[1,0] neg_lo:[0,1] neg_hi:[0,1]
	v_pk_add_f32 v[46:47], v[46:47], v[136:137] op_sel_hi:[1,0] neg_lo:[0,1] neg_hi:[0,1]
	v_pk_mul_f32 v[132:133], v[32:33], v[32:33]
	v_pk_fma_f32 v[132:133], v[34:35], v[34:35], v[132:133]
	v_pk_fma_f32 v[132:133], v[36:37], v[36:37], v[132:133]
	v_pk_fma_f32 v[132:133], v[38:39], v[38:39], v[132:133]
	v_pk_fma_f32 v[132:133], v[40:41], v[40:41], v[132:133]
	v_pk_fma_f32 v[132:133], v[42:43], v[42:43], v[132:133]
	v_pk_fma_f32 v[132:133], v[44:45], v[44:45], v[132:133]
	v_pk_fma_f32 v[132:133], v[46:47], v[46:47], v[132:133]
	v_add_f32_e32 v132, v132, v133
	s_nop 1
	v_add_f32_dpp v132, v132, v132 row_ror:8 row_mask:0xf bank_mask:0xf bound_ctrl:1
	s_nop 1
	v_add_f32_dpp v132, v132, v132 row_ror:4 row_mask:0xf bank_mask:0xf bound_ctrl:1
	s_nop 1
	v_add_f32_dpp v132, v132, v132 row_ror:2 row_mask:0xf bank_mask:0xf bound_ctrl:1
	s_nop 1
	v_add_f32_dpp v132, v132, v132 row_ror:1 row_mask:0xf bank_mask:0xf bound_ctrl:1
	s_nop 0
	v_readlane_b32 s98, v132, 0
	v_readlane_b32 s99, v132, 16
	s_nop 0
	v_mov_b32_e32 v134, s98
	s_nop 0
	v_add_f32_e32 v134, s99, v134
	v_readlane_b32 s98, v132, 32
	v_readlane_b32 s99, v132, 48
	s_nop 0
	v_add_f32_e32 v134, s98, v134
	s_nop 0
	v_add_f32_e32 v132, s99, v134
	v_mov_b32_e32 v134, 0x3727c5ac
	v_fmac_f32_e32 v134, 0x3a800000, v132
	v_rsq_f32_e32 v138, v134
	s_nop 0
	v_pk_mul_f32 v[32:33], v[32:33], v[138:139] op_sel_hi:[1,0]
	v_pk_mul_f32 v[34:35], v[34:35], v[138:139] op_sel_hi:[1,0]
	v_pk_mul_f32 v[36:37], v[36:37], v[138:139] op_sel_hi:[1,0]
	v_pk_mul_f32 v[38:39], v[38:39], v[138:139] op_sel_hi:[1,0]
	v_pk_mul_f32 v[40:41], v[40:41], v[138:139] op_sel_hi:[1,0]
	v_pk_mul_f32 v[42:43], v[42:43], v[138:139] op_sel_hi:[1,0]
	v_pk_mul_f32 v[44:45], v[44:45], v[138:139] op_sel_hi:[1,0]
	v_pk_mul_f32 v[46:47], v[46:47], v[138:139] op_sel_hi:[1,0]
	v_pk_fma_f32 v[32:33], v[0:1], v[32:33], v[4:5]
	v_pk_fma_f32 v[34:35], v[2:3], v[34:35], v[6:7]
	v_pk_fma_f32 v[36:37], v[8:9], v[36:37], v[12:13]
	v_pk_fma_f32 v[38:39], v[10:11], v[38:39], v[14:15]
	v_pk_fma_f32 v[40:41], v[16:17], v[40:41], v[20:21]
	v_pk_fma_f32 v[42:43], v[18:19], v[42:43], v[22:23]
	v_pk_fma_f32 v[44:45], v[24:25], v[44:45], v[28:29]
	v_pk_fma_f32 v[46:47], v[26:27], v[46:47], v[30:31]
	v_mad_u64_u32 v[126:127], vcc, v142, v140, v[116:117]
	global_store_dwordx4 v[126:127], v[32:35], off offset:0
	global_store_dwordx4 v[126:127], v[36:39], off offset:1024
	global_store_dwordx4 v[126:127], v[40:43], off offset:2048
	global_store_dwordx4 v[126:127], v[44:47], off offset:3072
	s_waitcnt vmcnt(8)
	v_mad_u64_u32 v[126:127], vcc, v142, v141, v[118:119]
	v_pk_add_f32 v[98:99], v[98:99], 1.0 op_sel_hi:[1,0]
	v_pk_add_f32 v[100:101], v[100:101], 1.0 op_sel_hi:[1,0]
	v_pk_fma_f32 v[98:99], v[98:99], v[32:33], v[66:67]
	v_pk_fma_f32 v[100:101], v[100:101], v[34:35], v[68:69]
	v_cvt_pk_bf16_f32 v144, v98, v99
	v_cvt_pk_bf16_f32 v145, v100, v101
	global_store_dwordx2 v[126:127], v[144:145], off offset:0
	v_pk_add_f32 v[102:103], v[102:103], 1.0 op_sel_hi:[1,0]
	v_pk_add_f32 v[104:105], v[104:105], 1.0 op_sel_hi:[1,0]
	v_pk_fma_f32 v[102:103], v[102:103], v[36:37], v[86:87]
	v_pk_fma_f32 v[104:105], v[104:105], v[38:39], v[88:89]
	v_cvt_pk_bf16_f32 v146, v102, v103
	v_cvt_pk_bf16_f32 v147, v104, v105
	global_store_dwordx2 v[126:127], v[146:147], off offset:512
	v_pk_add_f32 v[106:107], v[106:107], 1.0 op_sel_hi:[1,0]
	v_pk_add_f32 v[108:109], v[108:109], 1.0 op_sel_hi:[1,0]
	v_pk_fma_f32 v[106:107], v[106:107], v[40:41], v[90:91]
	v_pk_fma_f32 v[108:109], v[108:109], v[42:43], v[92:93]
	v_cvt_pk_bf16_f32 v148, v106, v107
	v_cvt_pk_bf16_f32 v149, v108, v109
	global_store_dwordx2 v[126:127], v[148:149], off offset:1024
	v_pk_add_f32 v[110:111], v[110:111], 1.0 op_sel_hi:[1,0]
	v_pk_add_f32 v[112:113], v[112:113], 1.0 op_sel_hi:[1,0]
	v_pk_fma_f32 v[110:111], v[110:111], v[44:45], v[94:95]
	v_pk_fma_f32 v[112:113], v[112:113], v[46:47], v[96:97]
	v_cvt_pk_bf16_f32 v150, v110, v111
	v_cvt_pk_bf16_f32 v151, v112, v113
	global_store_dwordx2 v[126:127], v[150:151], off offset:1536
	s_bitcmp1_b32 s101, 1
	s_cselect_b32 s98, 1, s6
	s_add_u32 s100, s100, s98
	v_mov_b32_e32 v142, s100
	s_bitcmp1_b32 s101, 1
	s_cbranch_scc0 .Lln20_ck0
	s_mul_hi_u32 s98, s100, 0xcccccccd
	s_lshr_b32 s98, s98, 3
	s_mul_i32 s98, s98, 10
	s_cmp_lg_u32 s98, s100
	s_branch .Lln20_cd0

.Lln20_cd0:
	s_cbranch_scc0 .Lln20_done
	s_sub_u32 s98, s100, 0x1000
	s_lshr_b32 s98, s98, 12
	s_add_u32 s98, s98, 1
	s_cmp_gt_u32 s100, 0xfff
	s_cselect_b32 s98, s98, 0
	s_mul_i32 s98, s98, 0x6000
	s_mov_b32 s99, 0
	v_lshl_add_u64 v[128:129], v[120:121], 0, s[98:99]
	s_movk_i32 s98, 0x1000
	v_lshl_add_u64 v[130:131], v[128:129], 0, s[98:99]
	global_load_dwordx4 v[66:69], v[128:129], off offset:0
	global_load_dwordx4 v[86:89], v[128:129], off offset:1024
	global_load_dwordx4 v[90:93], v[128:129], off offset:2048
	global_load_dwordx4 v[94:97], v[128:129], off offset:3072
	global_load_dwordx4 v[98:101], v[130:131], off offset:0
	global_load_dwordx4 v[102:105], v[130:131], off offset:1024
	global_load_dwordx4 v[106:109], v[130:131], off offset:2048
	global_load_dwordx4 v[110:113], v[130:131], off offset:3072
	s_bitcmp1_b32 s101, 1
	s_cselect_b32 s98, 1, s6
	s_add_u32 s98, s100, s98
	s_min_u32 s98, s98, 0x4fff
	v_mov_b32_e32 v143, s98
	v_mad_u64_u32 v[126:127], vcc, v143, v140, v[116:117]
	global_load_dwordx4 v[32:35], v[126:127], off offset:0
	global_load_dwordx4 v[36:39], v[126:127], off offset:1024
	global_load_dwordx4 v[40:43], v[126:127], off offset:2048
	global_load_dwordx4 v[44:47], v[126:127], off offset:3072
	s_waitcnt vmcnt(20)
	v_pk_add_f32 v[132:133], v[48:49], v[50:51]
	v_pk_add_f32 v[132:133], v[132:133], v[52:53]
	v_pk_add_f32 v[132:133], v[132:133], v[54:55]
	v_pk_add_f32 v[132:133], v[132:133], v[56:57]
	v_pk_add_f32 v[132:133], v[132:133], v[58:59]
	v_pk_add_f32 v[132:133], v[132:133], v[60:61]
	v_pk_add_f32 v[132:133], v[132:133], v[62:63]
	v_add_f32_e32 v132, v132, v133
	s_nop 1
	v_add_f32_dpp v132, v132, v132 row_ror:8 row_mask:0xf bank_mask:0xf bound_ctrl:1
	s_nop 1
	v_add_f32_dpp v132, v132, v132 row_ror:4 row_mask:0xf bank_mask:0xf bound_ctrl:1
	s_nop 1
	v_add_f32_dpp v132, v132, v132 row_ror:2 row_mask:0xf bank_mask:0xf bound_ctrl:1
	s_nop 1
	v_add_f32_dpp v132, v132, v132 row_ror:1 row_mask:0xf bank_mask:0xf bound_ctrl:1
	s_nop 0
	v_readlane_b32 s98, v132, 0
	v_readlane_b32 s99, v132, 16
	s_nop 0
	v_mov_b32_e32 v134, s98
	s_nop 0
	v_add_f32_e32 v134, s99, v134
	v_readlane_b32 s98, v132, 32
	v_readlane_b32 s99, v132, 48
	s_nop 0
	v_add_f32_e32 v134, s98, v134
	s_nop 0
	v_add_f32_e32 v132, s99, v134
	v_mul_f32_e32 v136, 0x3a800000, v132
	v_pk_add_f32 v[48:49], v[48:49], v[136:137] op_sel_hi:[1,0] neg_lo:[0,1] neg_hi:[0,1]
	v_pk_add_f32 v[50:51], v[50:51], v[136:137] op_sel_hi:[1,0] neg_lo:[0,1] neg_hi:[0,1]
	v_pk_add_f32 v[52:53], v[52:53], v[136:137] op_sel_hi:[1,0] neg_lo:[0,1] neg_hi:[0,1]
	v_pk_add_f32 v[54:55], v[54:55], v[136:137] op_sel_hi:[1,0] neg_lo:[0,1] neg_hi:[0,1]
	v_pk_add_f32 v[56:57], v[56:57], v[136:137] op_sel_hi:[1,0] neg_lo:[0,1] neg_hi:[0,1]
	v_pk_add_f32 v[58:59], v[58:59], v[136:137] op_sel_hi:[1,0] neg_lo:[0,1] neg_hi:[0,1]
	v_pk_add_f32 v[60:61], v[60:61], v[136:137] op_sel_hi:[1,0] neg_lo:[0,1] neg_hi:[0,1]
	v_pk_add_f32 v[62:63], v[62:63], v[136:137] op_sel_hi:[1,0] neg_lo:[0,1] neg_hi:[0,1]
	v_pk_mul_f32 v[132:133], v[48:49], v[48:49]
	v_pk_fma_f32 v[132:133], v[50:51], v[50:51], v[132:133]
	v_pk_fma_f32 v[132:133], v[52:53], v[52:53], v[132:133]
	v_pk_fma_f32 v[132:133], v[54:55], v[54:55], v[132:133]
	v_pk_fma_f32 v[132:133], v[56:57], v[56:57], v[132:133]
	v_pk_fma_f32 v[132:133], v[58:59], v[58:59], v[132:133]
	v_pk_fma_f32 v[132:133], v[60:61], v[60:61], v[132:133]
	v_pk_fma_f32 v[132:133], v[62:63], v[62:63], v[132:133]
	v_add_f32_e32 v132, v132, v133
	s_nop 1
	v_add_f32_dpp v132, v132, v132 row_ror:8 row_mask:0xf bank_mask:0xf bound_ctrl:1
	s_nop 1
	v_add_f32_dpp v132, v132, v132 row_ror:4 row_mask:0xf bank_mask:0xf bound_ctrl:1
	s_nop 1
	v_add_f32_dpp v132, v132, v132 row_ror:2 row_mask:0xf bank_mask:0xf bound_ctrl:1
	s_nop 1
	v_add_f32_dpp v132, v132, v132 row_ror:1 row_mask:0xf bank_mask:0xf bound_ctrl:1
	s_nop 0
	v_readlane_b32 s98, v132, 0
	v_readlane_b32 s99, v132, 16
	s_nop 0
	v_mov_b32_e32 v134, s98
	s_nop 0
	v_add_f32_e32 v134, s99, v134
	v_readlane_b32 s98, v132, 32
	v_readlane_b32 s99, v132, 48
	s_nop 0
	v_add_f32_e32 v134, s98, v134
	s_nop 0
	v_add_f32_e32 v132, s99, v134
	v_mov_b32_e32 v134, 0x3727c5ac
	v_fmac_f32_e32 v134, 0x3a800000, v132
	v_rsq_f32_e32 v138, v134
	s_nop 0
	v_pk_mul_f32 v[48:49], v[48:49], v[138:139] op_sel_hi:[1,0]
	v_pk_mul_f32 v[50:51], v[50:51], v[138:139] op_sel_hi:[1,0]
	v_pk_mul_f32 v[52:53], v[52:53], v[138:139] op_sel_hi:[1,0]
	v_pk_mul_f32 v[54:55], v[54:55], v[138:139] op_sel_hi:[1,0]
	v_pk_mul_f32 v[56:57], v[56:57], v[138:139] op_sel_hi:[1,0]
	v_pk_mul_f32 v[58:59], v[58:59], v[138:139] op_sel_hi:[1,0]
	v_pk_mul_f32 v[60:61], v[60:61], v[138:139] op_sel_hi:[1,0]
	v_pk_mul_f32 v[62:63], v[62:63], v[138:139] op_sel_hi:[1,0]
	v_pk_fma_f32 v[48:49], v[0:1], v[48:49], v[4:5]
	v_pk_fma_f32 v[50:51], v[2:3], v[50:51], v[6:7]
	v_pk_fma_f32 v[52:53], v[8:9], v[52:53], v[12:13]
	v_pk_fma_f32 v[54:55], v[10:11], v[54:55], v[14:15]
	v_pk_fma_f32 v[56:57], v[16:17], v[56:57], v[20:21]
	v_pk_fma_f32 v[58:59], v[18:19], v[58:59], v[22:23]
	v_pk_fma_f32 v[60:61], v[24:25], v[60:61], v[28:29]
	v_pk_fma_f32 v[62:63], v[26:27], v[62:63], v[30:31]
	v_mad_u64_u32 v[126:127], vcc, v142, v140, v[116:117]
	global_store_dwordx4 v[126:127], v[48:51], off offset:0
	global_store_dwordx4 v[126:127], v[52:55], off offset:1024
	global_store_dwordx4 v[126:127], v[56:59], off offset:2048
	global_store_dwordx4 v[126:127], v[60:63], off offset:3072
	s_waitcnt vmcnt(8)
	v_mad_u64_u32 v[126:127], vcc, v142, v141, v[118:119]
	v_pk_add_f32 v[98:99], v[98:99], 1.0 op_sel_hi:[1,0]
	v_pk_add_f32 v[100:101], v[100:101], 1.0 op_sel_hi:[1,0]
	v_pk_fma_f32 v[98:99], v[98:99], v[48:49], v[66:67]
	v_pk_fma_f32 v[100:101], v[100:101], v[50:51], v[68:69]
	v_cvt_pk_bf16_f32 v144, v98, v99
	v_cvt_pk_bf16_f32 v145, v100, v101
	global_store_dwordx2 v[126:127], v[144:145], off offset:0
	v_pk_add_f32 v[102:103], v[102:103], 1.0 op_sel_hi:[1,0]
	v_pk_add_f32 v[104:105], v[104:105], 1.0 op_sel_hi:[1,0]
	v_pk_fma_f32 v[102:103], v[102:103], v[52:53], v[86:87]
	v_pk_fma_f32 v[104:105], v[104:105], v[54:55], v[88:89]
	v_cvt_pk_bf16_f32 v146, v102, v103
	v_cvt_pk_bf16_f32 v147, v104, v105
	global_store_dwordx2 v[126:127], v[146:147], off offset:512
	v_pk_add_f32 v[106:107], v[106:107], 1.0 op_sel_hi:[1,0]
	v_pk_add_f32 v[108:109], v[108:109], 1.0 op_sel_hi:[1,0]
	v_pk_fma_f32 v[106:107], v[106:107], v[56:57], v[90:91]
	v_pk_fma_f32 v[108:109], v[108:109], v[58:59], v[92:93]
	v_cvt_pk_bf16_f32 v148, v106, v107
	v_cvt_pk_bf16_f32 v149, v108, v109
	global_store_dwordx2 v[126:127], v[148:149], off offset:1024
	v_pk_add_f32 v[110:111], v[110:111], 1.0 op_sel_hi:[1,0]
	v_pk_add_f32 v[112:113], v[112:113], 1.0 op_sel_hi:[1,0]
	v_pk_fma_f32 v[110:111], v[110:111], v[60:61], v[94:95]
	v_pk_fma_f32 v[112:113], v[112:113], v[62:63], v[96:97]
	v_cvt_pk_bf16_f32 v150, v110, v111
	v_cvt_pk_bf16_f32 v151, v112, v113
	global_store_dwordx2 v[126:127], v[150:151], off offset:1536
	s_bitcmp1_b32 s101, 1
	s_cselect_b32 s98, 1, s6
	s_add_u32 s100, s100, s98
	v_mov_b32_e32 v142, s100
	s_bitcmp1_b32 s101, 1
	s_cbranch_scc0 .Lln20_ck1
	s_mul_hi_u32 s98, s100, 0xcccccccd
	s_lshr_b32 s98, s98, 3
	s_mul_i32 s98, s98, 10
	s_cmp_lg_u32 s98, s100
	s_branch .Lln20_cd1

.Lln20_done:
	s_branch .LBB0_2951
.LBB0_2951:
	s_or_b64 exec, exec, s[4:5]
	s_waitcnt vmcnt(0)
	s_barrier
	s_and_saveexec_b64 s[0:1], s[74:75]
	s_cbranch_execz .LBB0_3003
	v_mov_b32_e32 v0, 0x12000
	s_waitcnt vmcnt(0) expcnt(0) lgkmcnt(0)
	ds_read_b32 v2, v0
	v_mov_b32_e32 v0, 0x12004
	ds_read_b32 v0, v0
	s_waitcnt lgkmcnt(1)
	v_cmp_ne_u32_e32 vcc, 0, v2
	s_cbranch_vccnz .LBB0_2967
	s_add_u32 s4, s80, 0x1000
	s_addc_u32 s5, s81, 0
	s_add_u32 s6, s80, 0x1100
	s_addc_u32 s7, s81, 0
	s_add_u32 s8, s80, 0x1200
	s_addc_u32 s9, s81, 0
	s_mul_i32 s2, s69, s72
	s_add_u32 s10, s80, 0x1300
	s_mul_i32 s2, s2, s68
	s_addc_u32 s11, s81, 0
	s_mov_b32 s3, 1
	v_mov_b32_e32 v16, 0
	s_branch .LBB0_2955
